# post_phase LoRA loop: use op_sel broadcast instead of 16 register copies + per-read wait ladder
# speedup vs baseline: 1.0233x; 1.0006x over previous
; #define LAS __attribute__((address_space(3)))
; __device__ __forceinline__ void post_phase(Frame& F, const Args& a) {
;     ...
;         for (int d = 0; d < 64; d += 4) {
;             f32x2 wv[4];
; #pragma unroll
;             for (int q = 0; q < 4; ++q) wv[q] = *(const f32x2*)(g2 + (d + q) * 1024 + c0);
; #pragma unroll
;             for (int tt = 0; tt < TT; ++tt) { const f32x4 xv = *(const LAS f32x4*)(xg + tt * 64 + d);
; #pragma unroll
;                 for (int q = 0; q < 4; ++q) gg[tt] += wv[q] * xv[q]; }
;         }
;         LAS float* gl = xg + 16 * 64;
; #pragma unroll
;         for (int tt = 0; tt < TT; ++tt) *(LAS f32x2*)(gl + tt * 1024 + c0) = gg[tt];
.LBB0_1245:
	global_load_dwordx2 v[52:53], v[0:1], off
	v_add_co_u32_e32 v64, vcc, s24, v0
	v_mov_b32_e32 v63, s7
	s_nop 0
	v_addc_co_u32_e32 v65, vcc, 0, v1, vcc
	v_add_co_u32_e32 v66, vcc, s25, v0
	s_add_i32 s6, s6, 4
	s_nop 0
	v_addc_co_u32_e32 v67, vcc, 0, v1, vcc
	global_load_dwordx2 v[128:129], v[64:65], off offset:-4096
	global_load_dwordx2 v[130:131], v[64:65], off
	global_load_dwordx2 v[132:133], v[66:67], off
	ds_read_b128 v[64:67], v63
	ds_read_b128 v[68:71], v63 offset:256
	ds_read_b128 v[72:75], v63 offset:512
	ds_read_b128 v[76:79], v63 offset:768
	ds_read_b128 v[80:83], v63 offset:1024
	ds_read_b128 v[84:87], v63 offset:1280
	ds_read_b128 v[88:91], v63 offset:1536
	ds_read_b128 v[92:95], v63 offset:1792
	ds_read_b128 v[96:99], v63 offset:2048
	ds_read_b128 v[100:103], v63 offset:2304
	ds_read_b128 v[104:107], v63 offset:2560
	ds_read_b128 v[108:111], v63 offset:2816
	ds_read_b128 v[112:115], v63 offset:3072
	ds_read_b128 v[116:119], v63 offset:3328
	ds_read_b128 v[120:123], v63 offset:3584
	ds_read_b128 v[124:127], v63 offset:3840
	s_add_i32 s7, s7, 16
	s_waitcnt lgkmcnt(0)
	v_lshl_add_u64 v[0:1], v[0:1], 0, s[12:13]
	s_cmp_gt_u32 s6, 59
	s_waitcnt vmcnt(3)
	v_pk_fma_f32 v[2:3], v[52:53], v[64:65], v[2:3] op_sel_hi:[1,0,1]
	v_pk_fma_f32 v[4:5], v[52:53], v[68:69], v[4:5] op_sel_hi:[1,0,1]
	v_pk_fma_f32 v[6:7], v[52:53], v[72:73], v[6:7] op_sel_hi:[1,0,1]
	v_pk_fma_f32 v[26:27], v[52:53], v[76:77], v[26:27] op_sel_hi:[1,0,1]
	v_pk_fma_f32 v[28:29], v[52:53], v[80:81], v[28:29] op_sel_hi:[1,0,1]
	v_pk_fma_f32 v[30:31], v[52:53], v[84:85], v[30:31] op_sel_hi:[1,0,1]
	v_pk_fma_f32 v[32:33], v[52:53], v[88:89], v[32:33] op_sel_hi:[1,0,1]
	v_pk_fma_f32 v[34:35], v[52:53], v[92:93], v[34:35] op_sel_hi:[1,0,1]
	v_pk_fma_f32 v[36:37], v[52:53], v[96:97], v[36:37] op_sel_hi:[1,0,1]
	v_pk_fma_f32 v[38:39], v[52:53], v[100:101], v[38:39] op_sel_hi:[1,0,1]
	v_pk_fma_f32 v[40:41], v[52:53], v[104:105], v[40:41] op_sel_hi:[1,0,1]
	v_pk_fma_f32 v[42:43], v[52:53], v[108:109], v[42:43] op_sel_hi:[1,0,1]
	v_pk_fma_f32 v[44:45], v[52:53], v[112:113], v[44:45] op_sel_hi:[1,0,1]
	v_pk_fma_f32 v[46:47], v[52:53], v[116:117], v[46:47] op_sel_hi:[1,0,1]
	v_pk_fma_f32 v[48:49], v[52:53], v[120:121], v[48:49] op_sel_hi:[1,0,1]
	v_pk_fma_f32 v[50:51], v[52:53], v[124:125], v[50:51] op_sel_hi:[1,0,1]
	s_waitcnt vmcnt(2)
	v_pk_fma_f32 v[2:3], v[128:129], v[64:65], v[2:3] op_sel:[0,1,0]
	v_pk_fma_f32 v[4:5], v[128:129], v[68:69], v[4:5] op_sel:[0,1,0]
	v_pk_fma_f32 v[6:7], v[128:129], v[72:73], v[6:7] op_sel:[0,1,0]
	v_pk_fma_f32 v[26:27], v[128:129], v[76:77], v[26:27] op_sel:[0,1,0]
	v_pk_fma_f32 v[28:29], v[128:129], v[80:81], v[28:29] op_sel:[0,1,0]
	v_pk_fma_f32 v[30:31], v[128:129], v[84:85], v[30:31] op_sel:[0,1,0]
	v_pk_fma_f32 v[32:33], v[128:129], v[88:89], v[32:33] op_sel:[0,1,0]
	v_pk_fma_f32 v[34:35], v[128:129], v[92:93], v[34:35] op_sel:[0,1,0]
	v_pk_fma_f32 v[36:37], v[128:129], v[96:97], v[36:37] op_sel:[0,1,0]
	v_pk_fma_f32 v[38:39], v[128:129], v[100:101], v[38:39] op_sel:[0,1,0]
	v_pk_fma_f32 v[40:41], v[128:129], v[104:105], v[40:41] op_sel:[0,1,0]
	v_pk_fma_f32 v[42:43], v[128:129], v[108:109], v[42:43] op_sel:[0,1,0]
	v_pk_fma_f32 v[44:45], v[128:129], v[112:113], v[44:45] op_sel:[0,1,0]
	v_pk_fma_f32 v[46:47], v[128:129], v[116:117], v[46:47] op_sel:[0,1,0]
	v_pk_fma_f32 v[48:49], v[128:129], v[120:121], v[48:49] op_sel:[0,1,0]
	v_pk_fma_f32 v[50:51], v[128:129], v[124:125], v[50:51] op_sel:[0,1,0]
	s_waitcnt vmcnt(1)
	v_pk_fma_f32 v[2:3], v[130:131], v[66:67], v[2:3] op_sel_hi:[1,0,1]
	v_pk_fma_f32 v[4:5], v[130:131], v[70:71], v[4:5] op_sel_hi:[1,0,1]
	v_pk_fma_f32 v[6:7], v[130:131], v[74:75], v[6:7] op_sel_hi:[1,0,1]
	v_pk_fma_f32 v[26:27], v[130:131], v[78:79], v[26:27] op_sel_hi:[1,0,1]
	v_pk_fma_f32 v[28:29], v[130:131], v[82:83], v[28:29] op_sel_hi:[1,0,1]
	v_pk_fma_f32 v[30:31], v[130:131], v[86:87], v[30:31] op_sel_hi:[1,0,1]
	v_pk_fma_f32 v[32:33], v[130:131], v[90:91], v[32:33] op_sel_hi:[1,0,1]
	v_pk_fma_f32 v[34:35], v[130:131], v[94:95], v[34:35] op_sel_hi:[1,0,1]
	v_pk_fma_f32 v[36:37], v[130:131], v[98:99], v[36:37] op_sel_hi:[1,0,1]
	v_pk_fma_f32 v[38:39], v[130:131], v[102:103], v[38:39] op_sel_hi:[1,0,1]
	v_pk_fma_f32 v[40:41], v[130:131], v[106:107], v[40:41] op_sel_hi:[1,0,1]
	v_pk_fma_f32 v[42:43], v[130:131], v[110:111], v[42:43] op_sel_hi:[1,0,1]
	v_pk_fma_f32 v[44:45], v[130:131], v[114:115], v[44:45] op_sel_hi:[1,0,1]
	v_pk_fma_f32 v[46:47], v[130:131], v[118:119], v[46:47] op_sel_hi:[1,0,1]
	v_pk_fma_f32 v[48:49], v[130:131], v[122:123], v[48:49] op_sel_hi:[1,0,1]
	v_pk_fma_f32 v[50:51], v[130:131], v[126:127], v[50:51] op_sel_hi:[1,0,1]
	s_waitcnt vmcnt(0)
	v_pk_fma_f32 v[2:3], v[132:133], v[66:67], v[2:3] op_sel:[0,1,0]
	v_pk_fma_f32 v[4:5], v[132:133], v[70:71], v[4:5] op_sel:[0,1,0]
	v_pk_fma_f32 v[6:7], v[132:133], v[74:75], v[6:7] op_sel:[0,1,0]
	v_pk_fma_f32 v[26:27], v[132:133], v[78:79], v[26:27] op_sel:[0,1,0]
	v_pk_fma_f32 v[28:29], v[132:133], v[82:83], v[28:29] op_sel:[0,1,0]
	v_pk_fma_f32 v[30:31], v[132:133], v[86:87], v[30:31] op_sel:[0,1,0]
	v_pk_fma_f32 v[32:33], v[132:133], v[90:91], v[32:33] op_sel:[0,1,0]
	v_pk_fma_f32 v[34:35], v[132:133], v[94:95], v[34:35] op_sel:[0,1,0]
	v_pk_fma_f32 v[36:37], v[132:133], v[98:99], v[36:37] op_sel:[0,1,0]
	v_pk_fma_f32 v[38:39], v[132:133], v[102:103], v[38:39] op_sel:[0,1,0]
	v_pk_fma_f32 v[40:41], v[132:133], v[106:107], v[40:41] op_sel:[0,1,0]
	v_pk_fma_f32 v[42:43], v[132:133], v[110:111], v[42:43] op_sel:[0,1,0]
	v_pk_fma_f32 v[44:45], v[132:133], v[114:115], v[44:45] op_sel:[0,1,0]
	v_pk_fma_f32 v[46:47], v[132:133], v[118:119], v[46:47] op_sel:[0,1,0]
	v_pk_fma_f32 v[48:49], v[132:133], v[122:123], v[48:49] op_sel:[0,1,0]
	v_pk_fma_f32 v[50:51], v[132:133], v[126:127], v[50:51] op_sel:[0,1,0]
	s_cbranch_scc0 .LBB0_1245
	ds_write2st64_b64 v54, v[2:3], v[4:5] offset0:8 offset1:16
	ds_write2st64_b64 v54, v[6:7], v[26:27] offset0:24 offset1:32
	ds_write2st64_b64 v54, v[28:29], v[30:31] offset0:40 offset1:48
	ds_write2st64_b64 v54, v[32:33], v[34:35] offset0:56 offset1:64
	ds_write2st64_b64 v54, v[36:37], v[38:39] offset0:72 offset1:80
	ds_write2st64_b64 v54, v[40:41], v[42:43] offset0:88 offset1:96
	ds_write2st64_b64 v54, v[44:45], v[46:47] offset0:104 offset1:112
	ds_write_b64 v54, v[48:49] offset:61440
	ds_write_b64 v55, v[50:51] offset:61440
	s_mov_b32 s47, 0
	v_mov_b32_e32 v30, v55
	s_mov_b32 s14, s18
